# GEMM->GEMM seams (1,6,8,9,10,16): flag barrier among only the four workgroups that produce and consume a row tile; other local seams over the 32-workgroup group
# baseline (speedup 1.0000x reference)
; __device__ __forceinline__ unsigned xb_ld(unsigned* p)              { return __hip_atomic_load(p, __ATOMIC_RELAXED, __HIP_MEMORY_SCOPE_AGENT); }
; __device__ __forceinline__ unsigned xb_add(unsigned* p, unsigned v) { return __hip_atomic_fetch_add(p, v, __ATOMIC_RELAXED, __HIP_MEMORY_SCOPE_AGENT); }
; #define XB_SPIN(cond, bar) do { unsigned _sp = 0; while (cond) { __builtin_amdgcn_s_sleep(1); \
;     if ((++_sp & 255u) == 0u) { if (xb_ld(&(bar)[XB_TMO])) break; if (_sp > XB_SPIN_CAP) { atomicAdd(&(bar)[XB_TMO], 1u); break; } } } } while (0)
; #define FFN_UP(k, f, nin) if (IN(k)) { BUILD_RTAB(RT, T, 2 * FF, false, nin) EpiSwiglu E{U, RT}; \
;         run_gemm(lds, XB, (const bf16_t*)(ws + WS_WUP + (f) * WUP_STRIDE), T, 2 * FF, D, E); } SEAM(k);
; __device__ __forceinline__ void xcd_barrier(const XcdBarrier& b) {
;     asm volatile("s_waitcnt vmcnt(0)" ::: "memory");
;     __syncthreads();
;     if (threadIdx.x == 0) {
;         unsigned* bar = b.bar;
;         __builtin_amdgcn_s_waitcnt(0);
;         unsigned nloc = b.st[0], nx = b.st[1];
;         if (nloc == 0u) { xcd_barrier_complete(bar, b.x, nloc, nx); b.st[0] = nloc; b.st[1] = nx; }
;         const unsigned old = xb_add(&bar[XB_XSUB(b.x)], 1u);
;         const unsigned gen = old / nloc;
;         if (old + 1u == (gen + 1u) * nloc) {
;             __builtin_amdgcn_fence(__ATOMIC_RELEASE, "agent");
;             asm volatile("s_waitcnt vmcnt(0)" ::: "memory");
;             const unsigned og = xb_add(&bar[XB_TOP], 1u);
;             const unsigned tg = og / nx;
;             if (og + 1u == (tg + 1u) * nx) xb_add(&bar[XB_TOPGEN], 1u);
;             else XB_SPIN(xb_ld(&bar[XB_TOPGEN]) == tg, bar);
;             __builtin_amdgcn_fence(__ATOMIC_ACQUIRE, "agent");
;             xb_add(&bar[XB_XGEN(b.x)], 1u);
;             asm volatile("s_waitcnt vmcnt(0)" ::: "memory");
;         } else {
;             XB_SPIN(xb_ld(&bar[XB_XGEN(b.x)]) == gen, bar);
;             __builtin_amdgcn_fence(__ATOMIC_ACQUIRE, "agent");
;             asm volatile("s_waitcnt vmcnt(0)" ::: "memory");
;         }
;     }
;     __syncthreads();
; }
; __global__ void __launch_bounds__(NTHREADS, 2) mega_fwd(Args a) {
;     ...
;     FFN_UP(1, 0, 0)
.LBB0_231:
	s_cmp_gt_i32 s31, 2
	s_cselect_b64 s[0:1], -1, 0
	s_and_b64 s[4:5], s[6:7], s[0:1]
	s_andn2_b64 vcc, exec, s[4:5]
	s_cbranch_vccnz .LBB0_285
	s_waitcnt vmcnt(0)
	s_waitcnt vmcnt(0) lgkmcnt(0)
	s_barrier
	v_readlane_b32 s101, v249, 48
	v_readlane_b32 s100, v249, 18
	s_nop 3
	s_cmp_eq_u32 s101, 0
	s_cbranch_scc1 .Lfb_orig_0
	s_cmp_eq_u32 s100, 1
	s_cbranch_scc1 .Lfb_inv_0
	s_cmp_lg_u32 s100, 0
	s_cbranch_scc1 .Lfb_done_0
	s_lshr_b32 s100, s92, 3
	s_and_b32 s99, s100, 7
	s_lshl_b32 s99, s99, 7
	s_add_i32 s99, s99, 0x183a00
	s_lshr_b32 s100, s100, 3
	s_lshl_b32 s100, s100, 2
	s_add_i32 s100, s100, s99
	v_mov_b32_e32 v0, s100
	v_mov_b32_e32 v1, 1
	global_store_dword v0, v1, s[28:29]
	s_bfe_u32 s98, s92, 0x30006
	v_and_b32_e32 v0, 3, v196
	v_lshl_or_b32 v0, v0, 3, s98
	v_lshl_add_u32 v0, v0, 2, s99
	s_mov_b32 s101, 0

; __device__ __forceinline__ unsigned xb_ld(unsigned* p)              { return __hip_atomic_load(p, __ATOMIC_RELAXED, __HIP_MEMORY_SCOPE_AGENT); }
; __device__ __forceinline__ unsigned xb_add(unsigned* p, unsigned v) { return __hip_atomic_fetch_add(p, v, __ATOMIC_RELAXED, __HIP_MEMORY_SCOPE_AGENT); }
; #define XB_SPIN(cond, bar) do { unsigned _sp = 0; while (cond) { __builtin_amdgcn_s_sleep(1); \
;     if ((++_sp & 255u) == 0u) { if (xb_ld(&(bar)[XB_TMO])) break; if (_sp > XB_SPIN_CAP) { atomicAdd(&(bar)[XB_TMO], 1u); break; } } } } while (0)
; #define SEAM(k) do { if (IN(k) && IN((k) + 1)) xcd_barrier(xbar); } while (0)
; __device__ __forceinline__ void xcd_barrier(const XcdBarrier& b) {
;     asm volatile("s_waitcnt vmcnt(0)" ::: "memory");
;     __syncthreads();
;     if (threadIdx.x == 0) {
;         unsigned* bar = b.bar;
;         __builtin_amdgcn_s_waitcnt(0);
;         unsigned nloc = b.st[0], nx = b.st[1];
;         if (nloc == 0u) { xcd_barrier_complete(bar, b.x, nloc, nx); b.st[0] = nloc; b.st[1] = nx; }
;         const unsigned old = xb_add(&bar[XB_XSUB(b.x)], 1u);
;         const unsigned gen = old / nloc;
;         if (old + 1u == (gen + 1u) * nloc) {
;             __builtin_amdgcn_fence(__ATOMIC_RELEASE, "agent");
;             asm volatile("s_waitcnt vmcnt(0)" ::: "memory");
;             const unsigned og = xb_add(&bar[XB_TOP], 1u);
;             const unsigned tg = og / nx;
;             if (og + 1u == (tg + 1u) * nx) xb_add(&bar[XB_TOPGEN], 1u);
;             else XB_SPIN(xb_ld(&bar[XB_TOPGEN]) == tg, bar);
;             __builtin_amdgcn_fence(__ATOMIC_ACQUIRE, "agent");
;             xb_add(&bar[XB_XGEN(b.x)], 1u);
;             asm volatile("s_waitcnt vmcnt(0)" ::: "memory");
;         } else {
;             XB_SPIN(xb_ld(&bar[XB_XGEN(b.x)]) == gen, bar);
;             __builtin_amdgcn_fence(__ATOMIC_ACQUIRE, "agent");
;             asm volatile("s_waitcnt vmcnt(0)" ::: "memory");
;         }
;     }
;     __syncthreads();
; }
; __global__ void __launch_bounds__(NTHREADS, 2) mega_fwd(Args a) {
;     ...
;     if (IN(6)) { EpiGlu E{YB, a.in[20], CAT}; run_gemm(lds, YB, (const bf16_t*)(ws + WS_WGLU), T, 512, 512, E); }
;     SEAM(6);
.LBB0_631:
	s_cmp_gt_i32 s31, 7
	s_cselect_b64 s[0:1], -1, 0
	s_and_b64 s[4:5], s[6:7], s[0:1]
	s_andn2_b64 vcc, exec, s[4:5]
	s_cbranch_vccnz .LBB0_685
	s_waitcnt vmcnt(0)
	s_waitcnt vmcnt(0) lgkmcnt(0)
	s_barrier
	v_readlane_b32 s101, v249, 48
	v_readlane_b32 s100, v249, 18
	s_nop 3
	s_cmp_eq_u32 s101, 0
	s_cbranch_scc1 .Lfb_orig_4
	s_cmp_eq_u32 s100, 1
	s_cbranch_scc1 .Lfb_inv_4
	s_cmp_lg_u32 s100, 0
	s_cbranch_scc1 .Lfb_done_4
	s_lshr_b32 s100, s92, 3
	s_and_b32 s99, s100, 7
	s_lshl_b32 s99, s99, 7
	s_add_i32 s99, s99, 0x183a00
	s_lshr_b32 s100, s100, 3
	s_lshl_b32 s100, s100, 2
	s_add_i32 s100, s100, s99
	v_mov_b32_e32 v0, s100
	v_mov_b32_e32 v1, 5
	global_store_dword v0, v1, s[28:29]
	s_bfe_u32 s98, s92, 0x30006
	v_and_b32_e32 v0, 3, v196
	v_lshl_or_b32 v0, v0, 3, s98
	v_lshl_add_u32 v0, v0, 2, s99
	s_mov_b32 s101, 0

; __device__ __forceinline__ unsigned xb_ld(unsigned* p)              { return __hip_atomic_load(p, __ATOMIC_RELAXED, __HIP_MEMORY_SCOPE_AGENT); }
; __device__ __forceinline__ unsigned xb_add(unsigned* p, unsigned v) { return __hip_atomic_fetch_add(p, v, __ATOMIC_RELAXED, __HIP_MEMORY_SCOPE_AGENT); }
; #define XB_SPIN(cond, bar) do { unsigned _sp = 0; while (cond) { __builtin_amdgcn_s_sleep(1); \
;     if ((++_sp & 255u) == 0u) { if (xb_ld(&(bar)[XB_TMO])) break; if (_sp > XB_SPIN_CAP) { atomicAdd(&(bar)[XB_TMO], 1u); break; } } } } while (0)
; #define FFN_UP(k, f, nin) if (IN(k)) { BUILD_RTAB(RT, T, 2 * FF, false, nin) EpiSwiglu E{U, RT}; \
;         run_gemm(lds, XB, (const bf16_t*)(ws + WS_WUP + (f) * WUP_STRIDE), T, 2 * FF, D, E); } SEAM(k);
; __device__ __forceinline__ void xcd_barrier(const XcdBarrier& b) {
;     asm volatile("s_waitcnt vmcnt(0)" ::: "memory");
;     __syncthreads();
;     if (threadIdx.x == 0) {
;         unsigned* bar = b.bar;
;         __builtin_amdgcn_s_waitcnt(0);
;         unsigned nloc = b.st[0], nx = b.st[1];
;         if (nloc == 0u) { xcd_barrier_complete(bar, b.x, nloc, nx); b.st[0] = nloc; b.st[1] = nx; }
;         const unsigned old = xb_add(&bar[XB_XSUB(b.x)], 1u);
;         const unsigned gen = old / nloc;
;         if (old + 1u == (gen + 1u) * nloc) {
;             __builtin_amdgcn_fence(__ATOMIC_RELEASE, "agent");
;             asm volatile("s_waitcnt vmcnt(0)" ::: "memory");
;             const unsigned og = xb_add(&bar[XB_TOP], 1u);
;             const unsigned tg = og / nx;
;             if (og + 1u == (tg + 1u) * nx) xb_add(&bar[XB_TOPGEN], 1u);
;             else XB_SPIN(xb_ld(&bar[XB_TOPGEN]) == tg, bar);
;             __builtin_amdgcn_fence(__ATOMIC_ACQUIRE, "agent");
;             xb_add(&bar[XB_XGEN(b.x)], 1u);
;             asm volatile("s_waitcnt vmcnt(0)" ::: "memory");
;         } else {
;             XB_SPIN(xb_ld(&bar[XB_XGEN(b.x)]) == gen, bar);
;             __builtin_amdgcn_fence(__ATOMIC_ACQUIRE, "agent");
;             asm volatile("s_waitcnt vmcnt(0)" ::: "memory");
;         }
;     }
;     __syncthreads();
; }
; __global__ void __launch_bounds__(NTHREADS, 2) mega_fwd(Args a) {
;     ...
;     FFN_UP(8, 1, 2)
.LBB0_817:
	s_cmp_gt_i32 s31, 9
	s_cselect_b64 s[0:1], -1, 0
	s_and_b64 s[4:5], s[6:7], s[0:1]
	s_andn2_b64 vcc, exec, s[4:5]
	s_cbranch_vccnz .LBB0_871
	s_waitcnt vmcnt(0)
	s_waitcnt vmcnt(0) lgkmcnt(0)
	s_barrier
	v_readlane_b32 s101, v249, 48
	v_readlane_b32 s100, v249, 18
	s_nop 3
	s_cmp_eq_u32 s101, 0
	s_cbranch_scc1 .Lfb_orig_5
	s_cmp_eq_u32 s100, 1
	s_cbranch_scc1 .Lfb_inv_5
	s_cmp_lg_u32 s100, 0
	s_cbranch_scc1 .Lfb_done_5
	s_lshr_b32 s100, s92, 3
	s_and_b32 s99, s100, 7
	s_lshl_b32 s99, s99, 7
	s_add_i32 s99, s99, 0x183a00
	s_lshr_b32 s100, s100, 3
	s_lshl_b32 s100, s100, 2
	s_add_i32 s100, s100, s99
	v_mov_b32_e32 v0, s100
	v_mov_b32_e32 v1, 6
	global_store_dword v0, v1, s[28:29]
	s_bfe_u32 s98, s92, 0x30006
	v_and_b32_e32 v0, 3, v196
	v_lshl_or_b32 v0, v0, 3, s98
	v_lshl_add_u32 v0, v0, 2, s99
	s_mov_b32 s101, 0

; __device__ __forceinline__ unsigned xb_ld(unsigned* p)              { return __hip_atomic_load(p, __ATOMIC_RELAXED, __HIP_MEMORY_SCOPE_AGENT); }
; __device__ __forceinline__ unsigned xb_add(unsigned* p, unsigned v) { return __hip_atomic_fetch_add(p, v, __ATOMIC_RELAXED, __HIP_MEMORY_SCOPE_AGENT); }
; #define XB_SPIN(cond, bar) do { unsigned _sp = 0; while (cond) { __builtin_amdgcn_s_sleep(1); \
;     if ((++_sp & 255u) == 0u) { if (xb_ld(&(bar)[XB_TMO])) break; if (_sp > XB_SPIN_CAP) { atomicAdd(&(bar)[XB_TMO], 1u); break; } } } } while (0)
; #define FFN_DN(k, f, xin, nout) if (IN(k)) { EpiResid E{XB, 0.5f, SS + (nout) * SSN}; run_gemm(lds, U, (const bf16_t*)(ws + WS_WDN + (f) * WDN_STRIDE), T, D, FF, E); } SEAM(k);
; __device__ __forceinline__ void xcd_barrier(const XcdBarrier& b) {
;     asm volatile("s_waitcnt vmcnt(0)" ::: "memory");
;     __syncthreads();
;     if (threadIdx.x == 0) {
;         unsigned* bar = b.bar;
;         __builtin_amdgcn_s_waitcnt(0);
;         unsigned nloc = b.st[0], nx = b.st[1];
;         if (nloc == 0u) { xcd_barrier_complete(bar, b.x, nloc, nx); b.st[0] = nloc; b.st[1] = nx; }
;         const unsigned old = xb_add(&bar[XB_XSUB(b.x)], 1u);
;         const unsigned gen = old / nloc;
;         if (old + 1u == (gen + 1u) * nloc) {
;             __builtin_amdgcn_fence(__ATOMIC_RELEASE, "agent");
;             asm volatile("s_waitcnt vmcnt(0)" ::: "memory");
;             const unsigned og = xb_add(&bar[XB_TOP], 1u);
;             const unsigned tg = og / nx;
;             if (og + 1u == (tg + 1u) * nx) xb_add(&bar[XB_TOPGEN], 1u);
;             else XB_SPIN(xb_ld(&bar[XB_TOPGEN]) == tg, bar);
;             __builtin_amdgcn_fence(__ATOMIC_ACQUIRE, "agent");
;             xb_add(&bar[XB_XGEN(b.x)], 1u);
;             asm volatile("s_waitcnt vmcnt(0)" ::: "memory");
;         } else {
;             XB_SPIN(xb_ld(&bar[XB_XGEN(b.x)]) == gen, bar);
;             __builtin_amdgcn_fence(__ATOMIC_ACQUIRE, "agent");
;             asm volatile("s_waitcnt vmcnt(0)" ::: "memory");
;         }
;     }
;     __syncthreads();
; }
; __global__ void __launch_bounds__(NTHREADS, 2) mega_fwd(Args a) {
;     ...
;     FFN_DN(9, 1, X, 3)
.LBB0_918:
	s_cmp_gt_i32 s31, 10
	s_cselect_b64 s[0:1], -1, 0
	s_and_b64 s[4:5], s[8:9], s[0:1]
	s_andn2_b64 vcc, exec, s[4:5]
	s_cbranch_vccnz .LBB0_972
	s_waitcnt vmcnt(0)
	s_waitcnt vmcnt(0) lgkmcnt(0)
	s_barrier
	v_readlane_b32 s101, v249, 48
	v_readlane_b32 s100, v249, 18
	s_nop 3
	s_cmp_eq_u32 s101, 0
	s_cbranch_scc1 .Lfb_orig_6
	s_cmp_eq_u32 s100, 1
	s_cbranch_scc1 .Lfb_inv_6
	s_cmp_lg_u32 s100, 0
	s_cbranch_scc1 .Lfb_done_6
	s_lshr_b32 s100, s92, 3
	s_and_b32 s99, s100, 7
	s_lshl_b32 s99, s99, 7
	s_add_i32 s99, s99, 0x183a00
	s_lshr_b32 s100, s100, 3
	s_lshl_b32 s100, s100, 2
	s_add_i32 s100, s100, s99
	v_mov_b32_e32 v0, s100
	v_mov_b32_e32 v1, 7
	global_store_dword v0, v1, s[28:29]
	s_bfe_u32 s98, s92, 0x30006
	v_and_b32_e32 v0, 3, v196
	v_lshl_or_b32 v0, v0, 3, s98
	v_lshl_add_u32 v0, v0, 2, s99
	s_mov_b32 s101, 0

; __device__ __forceinline__ unsigned xb_ld(unsigned* p)              { return __hip_atomic_load(p, __ATOMIC_RELAXED, __HIP_MEMORY_SCOPE_AGENT); }
; __device__ __forceinline__ unsigned xb_add(unsigned* p, unsigned v) { return __hip_atomic_fetch_add(p, v, __ATOMIC_RELAXED, __HIP_MEMORY_SCOPE_AGENT); }
; #define XB_SPIN(cond, bar) do { unsigned _sp = 0; while (cond) { __builtin_amdgcn_s_sleep(1); \
;     if ((++_sp & 255u) == 0u) { if (xb_ld(&(bar)[XB_TMO])) break; if (_sp > XB_SPIN_CAP) { atomicAdd(&(bar)[XB_TMO], 1u); break; } } } } while (0)
; #define FFN_UP(k, f, nin) if (IN(k)) { BUILD_RTAB(RT, T, 2 * FF, false, nin) EpiSwiglu E{U, RT}; \
;         run_gemm(lds, XB, (const bf16_t*)(ws + WS_WUP + (f) * WUP_STRIDE), T, 2 * FF, D, E); } SEAM(k);
; __device__ __forceinline__ void xcd_barrier(const XcdBarrier& b) {
;     asm volatile("s_waitcnt vmcnt(0)" ::: "memory");
;     __syncthreads();
;     if (threadIdx.x == 0) {
;         unsigned* bar = b.bar;
;         __builtin_amdgcn_s_waitcnt(0);
;         unsigned nloc = b.st[0], nx = b.st[1];
;         if (nloc == 0u) { xcd_barrier_complete(bar, b.x, nloc, nx); b.st[0] = nloc; b.st[1] = nx; }
;         const unsigned old = xb_add(&bar[XB_XSUB(b.x)], 1u);
;         const unsigned gen = old / nloc;
;         if (old + 1u == (gen + 1u) * nloc) {
;             __builtin_amdgcn_fence(__ATOMIC_RELEASE, "agent");
;             asm volatile("s_waitcnt vmcnt(0)" ::: "memory");
;             const unsigned og = xb_add(&bar[XB_TOP], 1u);
;             const unsigned tg = og / nx;
;             if (og + 1u == (tg + 1u) * nx) xb_add(&bar[XB_TOPGEN], 1u);
;             else XB_SPIN(xb_ld(&bar[XB_TOPGEN]) == tg, bar);
;             __builtin_amdgcn_fence(__ATOMIC_ACQUIRE, "agent");
;             xb_add(&bar[XB_XGEN(b.x)], 1u);
;             asm volatile("s_waitcnt vmcnt(0)" ::: "memory");
;         } else {
;             XB_SPIN(xb_ld(&bar[XB_XGEN(b.x)]) == gen, bar);
;             __builtin_amdgcn_fence(__ATOMIC_ACQUIRE, "agent");
;             asm volatile("s_waitcnt vmcnt(0)" ::: "memory");
;         }
;     }
;     __syncthreads();
; }
; __global__ void __launch_bounds__(NTHREADS, 2) mega_fwd(Args a) {
;     ...
;     FFN_UP(10, 2, 3)
.LBB0_1007:
	s_cmp_gt_i32 s31, 11
	s_cselect_b64 s[0:1], -1, 0
	s_and_b64 s[4:5], s[6:7], s[0:1]
	s_andn2_b64 vcc, exec, s[4:5]
	s_cbranch_vccnz .LBB0_1061
	s_waitcnt vmcnt(0)
	s_waitcnt vmcnt(0) lgkmcnt(0)
	s_barrier
	v_readlane_b32 s101, v249, 48
	v_readlane_b32 s100, v249, 18
	s_nop 3
	s_cmp_eq_u32 s101, 0
	s_cbranch_scc1 .Lfb_orig_7
	s_cmp_eq_u32 s100, 1
	s_cbranch_scc1 .Lfb_inv_7
	s_cmp_lg_u32 s100, 0
	s_cbranch_scc1 .Lfb_done_7
	s_lshr_b32 s100, s92, 3
	s_and_b32 s99, s100, 7
	s_lshl_b32 s99, s99, 7
	s_add_i32 s99, s99, 0x183a00
	s_lshr_b32 s100, s100, 3
	s_lshl_b32 s100, s100, 2
	s_add_i32 s100, s100, s99
	v_mov_b32_e32 v0, s100
	v_mov_b32_e32 v1, 8
	global_store_dword v0, v1, s[28:29]
	s_bfe_u32 s98, s92, 0x30006
	v_and_b32_e32 v0, 3, v196
	v_lshl_or_b32 v0, v0, 3, s98
	v_lshl_add_u32 v0, v0, 2, s99
	s_mov_b32 s101, 0

; __device__ __forceinline__ unsigned xb_ld(unsigned* p)              { return __hip_atomic_load(p, __ATOMIC_RELAXED, __HIP_MEMORY_SCOPE_AGENT); }
; __device__ __forceinline__ unsigned xb_add(unsigned* p, unsigned v) { return __hip_atomic_fetch_add(p, v, __ATOMIC_RELAXED, __HIP_MEMORY_SCOPE_AGENT); }
; #define XB_SPIN(cond, bar) do { unsigned _sp = 0; while (cond) { __builtin_amdgcn_s_sleep(1); \
;     if ((++_sp & 255u) == 0u) { if (xb_ld(&(bar)[XB_TMO])) break; if (_sp > XB_SPIN_CAP) { atomicAdd(&(bar)[XB_TMO], 1u); break; } } } } while (0)
; #define FFN_UP(k, f, nin) if (IN(k)) { BUILD_RTAB(RT, T, 2 * FF, false, nin) EpiSwiglu E{U, RT}; \
;         run_gemm(lds, XB, (const bf16_t*)(ws + WS_WUP + (f) * WUP_STRIDE), T, 2 * FF, D, E); } SEAM(k);
; __device__ __forceinline__ void xcd_barrier(const XcdBarrier& b) {
;     asm volatile("s_waitcnt vmcnt(0)" ::: "memory");
;     __syncthreads();
;     if (threadIdx.x == 0) {
;         unsigned* bar = b.bar;
;         __builtin_amdgcn_s_waitcnt(0);
;         unsigned nloc = b.st[0], nx = b.st[1];
;         if (nloc == 0u) { xcd_barrier_complete(bar, b.x, nloc, nx); b.st[0] = nloc; b.st[1] = nx; }
;         const unsigned old = xb_add(&bar[XB_XSUB(b.x)], 1u);
;         const unsigned gen = old / nloc;
;         if (old + 1u == (gen + 1u) * nloc) {
;             __builtin_amdgcn_fence(__ATOMIC_RELEASE, "agent");
;             asm volatile("s_waitcnt vmcnt(0)" ::: "memory");
;             const unsigned og = xb_add(&bar[XB_TOP], 1u);
;             const unsigned tg = og / nx;
;             if (og + 1u == (tg + 1u) * nx) xb_add(&bar[XB_TOPGEN], 1u);
;             else XB_SPIN(xb_ld(&bar[XB_TOPGEN]) == tg, bar);
;             __builtin_amdgcn_fence(__ATOMIC_ACQUIRE, "agent");
;             xb_add(&bar[XB_XGEN(b.x)], 1u);
;             asm volatile("s_waitcnt vmcnt(0)" ::: "memory");
;         } else {
;             XB_SPIN(xb_ld(&bar[XB_XGEN(b.x)]) == gen, bar);
;             __builtin_amdgcn_fence(__ATOMIC_ACQUIRE, "agent");
;             asm volatile("s_waitcnt vmcnt(0)" ::: "memory");
;         }
;     }
;     __syncthreads();
; }
; __global__ void __launch_bounds__(NTHREADS, 2) mega_fwd(Args a) {
;     ...
;     FFN_UP(16, 3, 5)
.LBB0_1747:
	s_cmp_gt_i32 s31, 17
	s_cselect_b64 s[0:1], -1, 0
	s_and_b64 s[4:5], s[6:7], s[0:1]
	s_andn2_b64 vcc, exec, s[4:5]
	s_cbranch_vccnz .LBB0_1801
	s_waitcnt vmcnt(0)
	s_waitcnt vmcnt(0) lgkmcnt(0)
	s_barrier
	v_readlane_b32 s101, v249, 48
	v_readlane_b32 s100, v249, 18
	s_nop 3
	s_cmp_eq_u32 s101, 0
	s_cbranch_scc1 .Lfb_orig_10
	s_cmp_eq_u32 s100, 1
	s_cbranch_scc1 .Lfb_inv_10
	s_cmp_lg_u32 s100, 0
	s_cbranch_scc1 .Lfb_done_10
	s_lshr_b32 s100, s92, 3
	s_and_b32 s99, s100, 7
	s_lshl_b32 s99, s99, 7
	s_add_i32 s99, s99, 0x183a00
	s_lshr_b32 s100, s100, 3
	s_lshl_b32 s100, s100, 2
	s_add_i32 s100, s100, s99
	v_mov_b32_e32 v0, s100
	v_mov_b32_e32 v1, 11
	global_store_dword v0, v1, s[28:29]
	s_bfe_u32 s98, s92, 0x30006
	v_and_b32_e32 v0, 3, v196
	v_lshl_or_b32 v0, v0, 3, s98
	v_lshl_add_u32 v0, v0, 2, s99
	s_mov_b32 s101, 0
